# v203 + kernel-start kernarg loads issued together at entry (one SMEM round trip instead of two)
# speedup vs baseline: 1.0024x; 1.0024x over previous
_Z6mk_fwd4Args:
	s_load_dword s33, s[0:1], 0xa8
	s_load_dwordx16 s[12:27], s[0:1], 0x0
	s_load_dwordx16 s[36:51], s[0:1], 0x40
	s_load_dwordx8 s[52:59], s[0:1], 0x80
	s_mov_b32 s10, s2
	s_add_u32 s2, s0, 0xa8
	s_addc_u32 s3, s1, 0
	v_cmp_gt_u32_e32 vcc, 64, v0
	v_writelane_b32 v254, s2, 0
	s_nop 1
	v_writelane_b32 v254, s3, 1
	s_and_saveexec_b64 s[2:3], vcc
	v_lshl_add_u32 v1, v0, 2, 0
	v_add_u32_e32 v1, 0x25f00, v1
	v_mov_b32_e32 v2, 0
	ds_write_b32 v1, v2
	s_or_b64 exec, exec, s[2:3]
	s_load_dwordx2 s[60:61], s[0:1], 0xa0
	s_waitcnt lgkmcnt(0)
	s_barrier
	s_getreg_b32 s2, hwreg(HW_REG_XCC_ID, 0, 4)
	s_and_b32 s62, s2, 15
	v_cmp_eq_u32_e64 s[96:97], 0, v0
	s_and_saveexec_b64 s[2:3], s[96:97]
	s_cbranch_execz .LBB0_5
	s_mov_b64 s[4:5], exec
	v_mbcnt_lo_u32_b32 v1, s4, 0
	v_mbcnt_hi_u32_b32 v1, s5, v1
	v_cmp_eq_u32_e32 vcc, 0, v1
	s_and_b64 s[6:7], exec, vcc
	s_mov_b64 exec, s[6:7]
	s_cbranch_execz .LBB0_5
	s_lshl_b32 s6, s62, 8
	s_bcnt1_i32_b64 s7, s[4:5]
	s_getpc_b64 s[4:5]
	s_add_u32 s4, s4, g_ctl@rel32@lo+5124
	s_addc_u32 s5, s5, g_ctl@rel32@hi+5132
	v_mov_b32_e32 v1, s6
	v_mov_b32_e32 v2, s7
	global_atomic_add v1, v2, s[4:5]
.LBB0_5:
	s_or_b64 exec, exec, s[2:3]
	s_and_b32 s0, s33, 7
	s_cmp_lg_u32 s0, 0
	s_mov_b32 s0, s10
	s_waitcnt lgkmcnt(0)
	v_writelane_b32 v254, s12, 2
	v_readfirstlane_b32 s34, v0
	s_nop 0
	v_writelane_b32 v254, s13, 3
	v_writelane_b32 v254, s14, 4
	v_writelane_b32 v254, s15, 5
	v_writelane_b32 v254, s16, 6
	v_writelane_b32 v254, s17, 7
	v_writelane_b32 v254, s18, 8
	v_writelane_b32 v254, s19, 9
	v_writelane_b32 v254, s20, 10
	v_writelane_b32 v254, s21, 11
	v_writelane_b32 v254, s22, 12
	v_writelane_b32 v254, s23, 13
	v_writelane_b32 v254, s24, 14
	v_writelane_b32 v254, s25, 15
	v_writelane_b32 v254, s26, 16
	v_writelane_b32 v254, s27, 17
	v_writelane_b32 v254, s0, 18
	s_nop 1
	v_writelane_b32 v254, s1, 19
	s_cbranch_scc1 .LBB0_7
	s_ashr_i32 s1, s10, 31
	s_lshr_b32 s1, s1, 29
	s_add_i32 s1, s10, s1
	s_and_b32 s2, s1, -8
	s_ashr_i32 s0, s33, 3
	s_sub_i32 s2, s10, s2
	s_mul_i32 s0, s0, s2
	s_ashr_i32 s1, s1, 3
	s_add_i32 s0, s0, s1
	v_writelane_b32 v254, s0, 18
	s_nop 1
	v_writelane_b32 v254, s1, 19
